# main NA tile loop: QK^T LDS fragment reads issued two k-steps ahead (two alternating register sets) instead of read-wait-mfma per step
# baseline (speedup 1.0000x reference)
; __device__ __forceinline__ void partialSM(f32x16& p0, f32x16& p1, float& m_reg, float& mn, float& alpha) {
;     ...
;   float pmax = p0[0];
; #pragma unroll
;   for (int r = 1; r < 16; ++r) pmax = fmaxf(pmax, p0[r]);
; #pragma unroll
;   for (int r = 0; r < 16; ++r) pmax = fmaxf(pmax, p1[r]);
;   { auto rr = __builtin_amdgcn_permlane32_swap(__float_as_uint(pmax), __float_as_uint(pmax), false, false);
;     pmax = fmaxf(__uint_as_float(rr[0]), __uint_as_float(rr[1])); }
;   if (__builtin_expect(__all(pmax - m_reg <= THR / SCALE), 1)) { mn = m_reg; alpha = 1.f; }
;   else { mn = fmaxf(m_reg, pmax); alpha = __builtin_amdgcn_exp2f((m_reg - mn) * C); m_reg = mn; }
; __device__ __forceinline__ void qkt(f32x16& p0, f32x16& p1, const bf16* Ks, const bf16x8* qs, int r32, int hi) {
; #pragma unroll
;   for (int d0 = 0; d0 < 8; ++d0) { int cb = (d0 * 16 + hi * 8) * 2; const bf16x8 q = qs[d0 * 64];
;     bf16x8 b0 = *reinterpret_cast<const bf16x8*>((const char*)Ks + NA_KSWZ(r32, cb));
;     bf16x8 b1 = *reinterpret_cast<const bf16x8*>((const char*)Ks + NA_KSWZ(32 + r32, cb));
;     p0 = __builtin_amdgcn_mfma_f32_32x32x16_bf16(b0, q, p0, 0, 0, 0);
;     p1 = __builtin_amdgcn_mfma_f32_32x32x16_bf16(b1, q, p1, 0, 0, 0); }
; }
.LBB0_718:
	v_add3_u32 v163, s18, v142, v141
	v_add3_u32 v210, s18, v143, v141
	v_add3_u32 v211, s18, v144, v141
	v_add3_u32 v212, s18, v145, v141
	v_add3_u32 v213, s18, v146, v141
	v_add3_u32 v214, s18, v147, v141
	v_add3_u32 v215, s18, v148, v141
	v_add3_u32 v216, s18, v149, v141
	ds_read_b128 v[164:167], v157
	ds_read_b128 v[168:171], v163 offset:32768
	ds_read_b128 v[172:175], v163 offset:40960
	ds_read_b128 v[198:201], v157 offset:1024
	ds_read_b128 v[202:205], v210 offset:32768
	ds_read_b128 v[206:209], v210 offset:40960
	s_waitcnt lgkmcnt(4)
	v_mfma_f32_32x32x16_bf16 v[84:99], v[168:171], v[164:167], v[84:99]
	s_waitcnt lgkmcnt(3)
	v_mfma_f32_32x32x16_bf16 v[68:83], v[172:175], v[164:167], v[68:83]
	ds_read_b128 v[164:167], v157 offset:2048
	ds_read_b128 v[168:171], v211 offset:32768
	ds_read_b128 v[172:175], v211 offset:40960
	s_waitcnt lgkmcnt(4)
	v_mfma_f32_32x32x16_bf16 v[84:99], v[202:205], v[198:201], v[84:99]
	s_waitcnt lgkmcnt(3)
	v_mfma_f32_32x32x16_bf16 v[68:83], v[206:209], v[198:201], v[68:83]
	ds_read_b128 v[198:201], v157 offset:3072
	ds_read_b128 v[202:205], v212 offset:32768
	ds_read_b128 v[206:209], v212 offset:40960
	s_waitcnt lgkmcnt(4)
	v_mfma_f32_32x32x16_bf16 v[84:99], v[168:171], v[164:167], v[84:99]
	s_waitcnt lgkmcnt(3)
	v_mfma_f32_32x32x16_bf16 v[68:83], v[172:175], v[164:167], v[68:83]
	ds_read_b128 v[164:167], v157 offset:4096
	ds_read_b128 v[168:171], v213 offset:32768
	ds_read_b128 v[172:175], v213 offset:40960
	s_waitcnt lgkmcnt(4)
	v_mfma_f32_32x32x16_bf16 v[84:99], v[202:205], v[198:201], v[84:99]
	s_waitcnt lgkmcnt(3)
	v_mfma_f32_32x32x16_bf16 v[68:83], v[206:209], v[198:201], v[68:83]
	ds_read_b128 v[198:201], v157 offset:5120
	ds_read_b128 v[202:205], v214 offset:32768
	ds_read_b128 v[206:209], v214 offset:40960
	s_waitcnt lgkmcnt(4)
	v_mfma_f32_32x32x16_bf16 v[84:99], v[168:171], v[164:167], v[84:99]
	s_waitcnt lgkmcnt(3)
	v_mfma_f32_32x32x16_bf16 v[68:83], v[172:175], v[164:167], v[68:83]
	ds_read_b128 v[164:167], v157 offset:6144
	ds_read_b128 v[168:171], v215 offset:32768
	ds_read_b128 v[172:175], v215 offset:40960
	s_waitcnt lgkmcnt(4)
	v_mfma_f32_32x32x16_bf16 v[84:99], v[202:205], v[198:201], v[84:99]
	s_waitcnt lgkmcnt(3)
	v_mfma_f32_32x32x16_bf16 v[68:83], v[206:209], v[198:201], v[68:83]
	ds_read_b128 v[198:201], v157 offset:7168
	ds_read_b128 v[202:205], v216 offset:32768
	ds_read_b128 v[206:209], v216 offset:40960
	s_waitcnt lgkmcnt(4)
	v_mfma_f32_32x32x16_bf16 v[84:99], v[168:171], v[164:167], v[84:99]
	s_waitcnt lgkmcnt(3)
	v_mfma_f32_32x32x16_bf16 v[68:83], v[172:175], v[164:167], v[68:83]
	s_waitcnt lgkmcnt(1)
	v_mfma_f32_32x32x16_bf16 v[84:99], v[202:205], v[198:201], v[84:99]
	s_waitcnt lgkmcnt(0)
	v_mfma_f32_32x32x16_bf16 v[68:83], v[206:209], v[198:201], v[68:83]
	s_nop 9
	v_max_f32_e32 v163, v85, v85
	v_max_f32_e32 v164, v84, v84
	v_max_f32_e32 v163, v164, v163
	v_max3_f32 v163, v163, v86, v87
	v_max3_f32 v163, v163, v88, v89
	v_max3_f32 v163, v163, v90, v91
	v_max3_f32 v163, v163, v92, v93
	v_max3_f32 v163, v163, v94, v95
	v_max3_f32 v163, v163, v96, v97
	v_max3_f32 v163, v163, v98, v99
	v_max3_f32 v163, v163, v68, v69
	v_max3_f32 v163, v163, v70, v71
	v_max3_f32 v163, v163, v72, v73
	v_max3_f32 v163, v163, v74, v75
	v_max3_f32 v163, v163, v76, v77
	v_max3_f32 v163, v163, v78, v79
	v_max3_f32 v163, v163, v80, v81
	v_max3_f32 v163, v163, v82, v83
	v_mov_b32_e32 v164, v163
	s_nop 1
	v_permlane32_swap_b32_e32 v163, v164
	v_max_f32_e32 v164, v164, v164
	v_max_f32_e32 v163, v163, v163
	v_max_f32_e32 v163, v163, v164
	v_sub_f32_e32 v164, v163, v129
	v_cmp_ge_f32_e32 vcc, s35, v164
	v_max_f32_e32 v164, v129, v129
	v_max_f32_e32 v164, v164, v163
	v_sub_f32_e32 v163, v129, v164
	v_mul_f32_e32 v163, 0x3e0293ee, v163
	v_exp_f32_e32 v163, v163
	s_cmp_eq_u64 vcc, exec
	s_cselect_b64 s[4:5], -1, 0
	v_cndmask_b32_e64 v163, v163, 1.0, s[4:5]
	v_cmp_gt_f32_e32 vcc, 1.0, v163
	s_cbranch_vccz .LBB0_709
	s_and_saveexec_b64 s[18:19], s[44:45]
	s_cbranch_execz .LBB0_708
	ds_write_b32 v150, v163 offset:128
	s_branch .LBB0_708
